# v112 with SwiGLU epilogue priority level 3 instead of 2 (priority level sweep)
# speedup vs baseline: 1.0025x; 1.0025x over previous
; __device__ __forceinline__ float siluf_(float x) { return x * __builtin_amdgcn_rcpf(1.f + __expf(-x)); }
;     ...
;           for (int mi = 0; mi < MI; mi++)
; #pragma unroll
;             for (int ni = 0; ni < 4; ni++)
;               acc[mi][ni] = __builtin_amdgcn_mfma_f32_16x16x32_bf16(bfr[ni], af[mi], acc[mi][ni], 0, 0, 0);
;     ...
;         } else if constexpr (EPI == EPI_SWIGLU) {
; #pragma unroll
;           for (int np = 0; np < 2; np++) {
;             const unsigned hc = ((unsigned)(n0 + wn * 64) >> 1) + np * 16 + fq * 4;
;             const f32x4 g = acc[mi][2 * np], u = acc[mi][2 * np + 1];
;             uint2 o;
;             o.x = pack2(siluf_(g[0]) * u[0], siluf_(g[1]) * u[1]);
;             o.y = pack2(siluf_(g[2]) * u[2], siluf_(g[3]) * u[3]);
;             *(uint2*)(e.b0 + (row * (unsigned)DFF + hc)) = o;
;           }
.Lsw_last:
	v_mfma_f32_16x16x32_bf16 v[134:137], v[194:197], v[156:159], v[134:137]
	v_mfma_f32_16x16x32_bf16 v[130:133], v[198:201], v[156:159], v[130:133]
	v_mfma_f32_16x16x32_bf16 v[126:129], v[202:205], v[156:159], v[126:129]
	v_mfma_f32_16x16x32_bf16 v[122:125], v[226:229], v[156:159], v[122:125]
	v_mfma_f32_16x16x32_bf16 v[118:121], v[194:197], v[166:169], v[118:121]
	v_mfma_f32_16x16x32_bf16 v[114:117], v[198:201], v[166:169], v[114:117]
	v_mfma_f32_16x16x32_bf16 v[110:113], v[202:205], v[166:169], v[110:113]
	v_mfma_f32_16x16x32_bf16 v[106:109], v[226:229], v[166:169], v[106:109]
	v_mfma_f32_16x16x32_bf16 v[102:105], v[194:197], v[170:173], v[102:105]
	v_mfma_f32_16x16x32_bf16 v[98:101], v[198:201], v[170:173], v[98:101]
	v_mfma_f32_16x16x32_bf16 v[94:97], v[202:205], v[170:173], v[94:97]
	v_mfma_f32_16x16x32_bf16 v[90:93], v[226:229], v[170:173], v[90:93]
	v_mfma_f32_16x16x32_bf16 v[86:89], v[194:197], v[174:177], v[86:89]
	v_mfma_f32_16x16x32_bf16 v[82:85], v[198:201], v[174:177], v[82:85]
	v_mfma_f32_16x16x32_bf16 v[78:81], v[202:205], v[174:177], v[78:81]
	v_mfma_f32_16x16x32_bf16 v[74:77], v[226:229], v[174:177], v[74:77]
	v_mfma_f32_16x16x32_bf16 v[70:73], v[194:197], v[178:181], v[70:73]
	v_mfma_f32_16x16x32_bf16 v[66:69], v[198:201], v[178:181], v[66:69]
	v_mfma_f32_16x16x32_bf16 v[62:65], v[202:205], v[178:181], v[62:65]
	v_mfma_f32_16x16x32_bf16 v[58:61], v[226:229], v[178:181], v[58:61]
	v_mfma_f32_16x16x32_bf16 v[54:57], v[194:197], v[182:185], v[54:57]
	v_mfma_f32_16x16x32_bf16 v[50:53], v[198:201], v[182:185], v[50:53]
	v_mfma_f32_16x16x32_bf16 v[46:49], v[202:205], v[182:185], v[46:49]
	v_mfma_f32_16x16x32_bf16 v[42:45], v[226:229], v[182:185], v[42:45]
	v_mfma_f32_16x16x32_bf16 v[38:41], v[194:197], v[186:189], v[38:41]
	v_mfma_f32_16x16x32_bf16 v[34:37], v[198:201], v[186:189], v[34:37]
	v_mfma_f32_16x16x32_bf16 v[30:33], v[202:205], v[186:189], v[30:33]
	v_mfma_f32_16x16x32_bf16 v[26:29], v[226:229], v[186:189], v[26:29]
	v_mfma_f32_16x16x32_bf16 v[22:25], v[194:197], v[190:193], v[22:25]
	v_mfma_f32_16x16x32_bf16 v[18:21], v[198:201], v[190:193], v[18:21]
	v_mfma_f32_16x16x32_bf16 v[14:17], v[202:205], v[190:193], v[14:17]
	v_mfma_f32_16x16x32_bf16 v[10:13], v[226:229], v[190:193], v[10:13]
	s_setprio 3
	v_or_b32_e32 v8, s8, v148
	v_lshrrev_b32_e32 v8, 1, v8
	v_add_u32_e32 v142, s7, v150
	v_or_b32_e32 v8, v8, v149
	s_movk_i32 s4, 0xb00
	v_mad_u64_u32 v[142:143], s[4:5], v142, s4, v[8:9]
	v_bfe_u32 v144, v2, 4, 1
	v_mul_u32_u24_e32 v144, 12, v144
	s_nop 0
	v_add_u32_e32 v142, v142, v144
	v_mul_f32_e32 v174, 0xbfb8aa3b, v134
	v_mul_f32_e32 v175, 0xbfb8aa3b, v135
	v_mul_f32_e32 v176, 0xbfb8aa3b, v136
	v_mul_f32_e32 v177, 0xbfb8aa3b, v137
	v_mul_f32_e32 v178, 0xbfb8aa3b, v126
	v_mul_f32_e32 v179, 0xbfb8aa3b, v127
	v_mul_f32_e32 v180, 0xbfb8aa3b, v128
	v_mul_f32_e32 v181, 0xbfb8aa3b, v129
	v_exp_f32_e32 v174, v174
	v_exp_f32_e32 v175, v175
	v_exp_f32_e32 v176, v176
	v_exp_f32_e32 v177, v177
	v_exp_f32_e32 v178, v178
	v_exp_f32_e32 v179, v179
	v_exp_f32_e32 v180, v180
	v_exp_f32_e32 v181, v181
	v_add_f32_e32 v174, 1.0, v174
	v_add_f32_e32 v175, 1.0, v175
	v_add_f32_e32 v176, 1.0, v176
	v_add_f32_e32 v177, 1.0, v177
	v_add_f32_e32 v178, 1.0, v178
	v_add_f32_e32 v179, 1.0, v179
	v_add_f32_e32 v180, 1.0, v180
	v_add_f32_e32 v181, 1.0, v181
	v_rcp_f32_e32 v174, v174
	v_rcp_f32_e32 v175, v175
	v_rcp_f32_e32 v176, v176
	v_rcp_f32_e32 v177, v177
	v_rcp_f32_e32 v178, v178
	v_rcp_f32_e32 v179, v179
	v_rcp_f32_e32 v180, v180
	v_rcp_f32_e32 v181, v181
	v_mov_b32_e32 v8, v142
	v_pk_mul_f32 v[134:135], v[134:135], v[174:175]
	v_pk_mul_f32 v[136:137], v[136:137], v[176:177]
	v_pk_mul_f32 v[126:127], v[126:127], v[178:179]
	v_pk_mul_f32 v[128:129], v[128:129], v[180:181]
	v_lshl_add_u64 v[182:183], v[8:9], 1, s[52:53]
	v_pk_mul_f32 v[130:131], v[130:131], v[134:135]
	v_pk_mul_f32 v[132:133], v[132:133], v[136:137]
	v_pk_mul_f32 v[122:123], v[122:123], v[126:127]
	v_pk_mul_f32 v[124:125], v[124:125], v[128:129]
	v_cvt_pk_bf16_f32 v166, v130, v131
	v_cvt_pk_bf16_f32 v167, v132, v133
	v_cvt_pk_bf16_f32 v168, v122, v123
	v_cvt_pk_bf16_f32 v169, v124, v125
	s_nop 1
	v_permlane16_swap_b32 v166, v168
	v_permlane16_swap_b32 v167, v169
	s_nop 1
	global_store_dwordx4 v[182:183], v[166:169], off
	v_mul_f32_e32 v174, 0xbfb8aa3b, v118
	v_mul_f32_e32 v175, 0xbfb8aa3b, v119
	v_mul_f32_e32 v176, 0xbfb8aa3b, v120
	v_mul_f32_e32 v177, 0xbfb8aa3b, v121
	v_mul_f32_e32 v178, 0xbfb8aa3b, v110
	v_mul_f32_e32 v179, 0xbfb8aa3b, v111
	v_mul_f32_e32 v180, 0xbfb8aa3b, v112
	v_mul_f32_e32 v181, 0xbfb8aa3b, v113
	v_exp_f32_e32 v174, v174
	v_exp_f32_e32 v175, v175
	v_exp_f32_e32 v176, v176
	v_exp_f32_e32 v177, v177
	v_exp_f32_e32 v178, v178
	v_exp_f32_e32 v179, v179
	v_exp_f32_e32 v180, v180
	v_exp_f32_e32 v181, v181
	v_add_f32_e32 v174, 1.0, v174
	v_add_f32_e32 v175, 1.0, v175
	v_add_f32_e32 v176, 1.0, v176
	v_add_f32_e32 v177, 1.0, v177
	v_add_f32_e32 v178, 1.0, v178
	v_add_f32_e32 v179, 1.0, v179
	v_add_f32_e32 v180, 1.0, v180
	v_add_f32_e32 v181, 1.0, v181
	v_rcp_f32_e32 v174, v174
	v_rcp_f32_e32 v175, v175
	v_rcp_f32_e32 v176, v176
	v_rcp_f32_e32 v177, v177
	v_rcp_f32_e32 v178, v178
	v_rcp_f32_e32 v179, v179
	v_rcp_f32_e32 v180, v180
	v_rcp_f32_e32 v181, v181
	v_add_u32_e32 v8, 0xb000, v142
	v_pk_mul_f32 v[118:119], v[118:119], v[174:175]
	v_pk_mul_f32 v[120:121], v[120:121], v[176:177]
	v_pk_mul_f32 v[110:111], v[110:111], v[178:179]
	v_pk_mul_f32 v[112:113], v[112:113], v[180:181]
	v_lshl_add_u64 v[184:185], v[8:9], 1, s[52:53]
	v_pk_mul_f32 v[114:115], v[114:115], v[118:119]
	v_pk_mul_f32 v[116:117], v[116:117], v[120:121]
	v_pk_mul_f32 v[106:107], v[106:107], v[110:111]
; __device__ __forceinline__ float siluf_(float x) { return x * __builtin_amdgcn_rcpf(1.f + __expf(-x)); }
;     ...
;         } else if constexpr (EPI == EPI_SWIGLU) {
; #pragma unroll
;           for (int np = 0; np < 2; np++) {
;             const unsigned hc = ((unsigned)(n0 + wn * 64) >> 1) + np * 16 + fq * 4;
;             const f32x4 g = acc[mi][2 * np], u = acc[mi][2 * np + 1];
;             uint2 o;
;             o.x = pack2(siluf_(g[0]) * u[0], siluf_(g[1]) * u[1]);
;             o.y = pack2(siluf_(g[2]) * u[2], siluf_(g[3]) * u[3]);
;             *(uint2*)(e.b0 + (row * (unsigned)DFF + hc)) = o;
;           }
	v_pk_mul_f32 v[108:109], v[108:109], v[112:113]
	v_cvt_pk_bf16_f32 v170, v114, v115
	v_cvt_pk_bf16_f32 v171, v116, v117
	v_cvt_pk_bf16_f32 v172, v106, v107
	v_cvt_pk_bf16_f32 v173, v108, v109
	s_nop 1
	v_permlane16_swap_b32 v170, v172
	v_permlane16_swap_b32 v171, v173
	s_nop 1
	global_store_dwordx4 v[184:185], v[170:173], off
	v_mul_f32_e32 v174, 0xbfb8aa3b, v102
	v_mul_f32_e32 v175, 0xbfb8aa3b, v103
	v_mul_f32_e32 v176, 0xbfb8aa3b, v104
	v_mul_f32_e32 v177, 0xbfb8aa3b, v105
	v_mul_f32_e32 v178, 0xbfb8aa3b, v94
	v_mul_f32_e32 v179, 0xbfb8aa3b, v95
	v_mul_f32_e32 v180, 0xbfb8aa3b, v96
	v_mul_f32_e32 v181, 0xbfb8aa3b, v97
	v_exp_f32_e32 v174, v174
	v_exp_f32_e32 v175, v175
	v_exp_f32_e32 v176, v176
	v_exp_f32_e32 v177, v177
	v_exp_f32_e32 v178, v178
	v_exp_f32_e32 v179, v179
	v_exp_f32_e32 v180, v180
	v_exp_f32_e32 v181, v181
	v_add_f32_e32 v174, 1.0, v174
	v_add_f32_e32 v175, 1.0, v175
	v_add_f32_e32 v176, 1.0, v176
	v_add_f32_e32 v177, 1.0, v177
	v_add_f32_e32 v178, 1.0, v178
	v_add_f32_e32 v179, 1.0, v179
	v_add_f32_e32 v180, 1.0, v180
	v_add_f32_e32 v181, 1.0, v181
	v_rcp_f32_e32 v174, v174
	v_rcp_f32_e32 v175, v175
	v_rcp_f32_e32 v176, v176
	v_rcp_f32_e32 v177, v177
	v_rcp_f32_e32 v178, v178
	v_rcp_f32_e32 v179, v179
	v_rcp_f32_e32 v180, v180
	v_rcp_f32_e32 v181, v181
	v_add_u32_e32 v8, 0x16000, v142
	v_pk_mul_f32 v[102:103], v[102:103], v[174:175]
	v_pk_mul_f32 v[104:105], v[104:105], v[176:177]
	v_pk_mul_f32 v[94:95], v[94:95], v[178:179]
	v_pk_mul_f32 v[96:97], v[96:97], v[180:181]
	v_lshl_add_u64 v[182:183], v[8:9], 1, s[52:53]
	v_pk_mul_f32 v[98:99], v[98:99], v[102:103]
	v_pk_mul_f32 v[100:101], v[100:101], v[104:105]
	v_pk_mul_f32 v[90:91], v[90:91], v[94:95]
	v_pk_mul_f32 v[92:93], v[92:93], v[96:97]
	v_cvt_pk_bf16_f32 v166, v98, v99
	v_cvt_pk_bf16_f32 v167, v100, v101
	v_cvt_pk_bf16_f32 v168, v90, v91
	v_cvt_pk_bf16_f32 v169, v92, v93
	s_nop 1
	v_permlane16_swap_b32 v166, v168
	v_permlane16_swap_b32 v167, v169
	s_nop 1
	global_store_dwordx4 v[182:183], v[166:169], off
	v_mul_f32_e32 v174, 0xbfb8aa3b, v86
	v_mul_f32_e32 v175, 0xbfb8aa3b, v87
	v_mul_f32_e32 v176, 0xbfb8aa3b, v88
	v_mul_f32_e32 v177, 0xbfb8aa3b, v89
	v_mul_f32_e32 v178, 0xbfb8aa3b, v78
	v_mul_f32_e32 v179, 0xbfb8aa3b, v79
	v_mul_f32_e32 v180, 0xbfb8aa3b, v80
	v_mul_f32_e32 v181, 0xbfb8aa3b, v81
	v_exp_f32_e32 v174, v174
	v_exp_f32_e32 v175, v175
	v_exp_f32_e32 v176, v176
	v_exp_f32_e32 v177, v177
	v_exp_f32_e32 v178, v178
	v_exp_f32_e32 v179, v179
	v_exp_f32_e32 v180, v180
	v_exp_f32_e32 v181, v181
	v_add_f32_e32 v174, 1.0, v174
	v_add_f32_e32 v175, 1.0, v175
	v_add_f32_e32 v176, 1.0, v176
	v_add_f32_e32 v177, 1.0, v177
	v_add_f32_e32 v178, 1.0, v178
	v_add_f32_e32 v179, 1.0, v179
	v_add_f32_e32 v180, 1.0, v180
	v_add_f32_e32 v181, 1.0, v181
	v_rcp_f32_e32 v174, v174
	v_rcp_f32_e32 v175, v175
	v_rcp_f32_e32 v176, v176
	v_rcp_f32_e32 v177, v177
	v_rcp_f32_e32 v178, v178
	v_rcp_f32_e32 v179, v179
	v_rcp_f32_e32 v180, v180
	v_rcp_f32_e32 v181, v181
	v_add_u32_e32 v8, 0x21000, v142
	v_pk_mul_f32 v[86:87], v[86:87], v[174:175]
	v_pk_mul_f32 v[88:89], v[88:89], v[176:177]
	v_pk_mul_f32 v[78:79], v[78:79], v[178:179]
	v_pk_mul_f32 v[80:81], v[80:81], v[180:181]
	v_lshl_add_u64 v[184:185], v[8:9], 1, s[52:53]
	v_pk_mul_f32 v[82:83], v[82:83], v[86:87]
	v_pk_mul_f32 v[84:85], v[84:85], v[88:89]
	v_pk_mul_f32 v[74:75], v[74:75], v[78:79]
	v_pk_mul_f32 v[76:77], v[76:77], v[80:81]
	v_cvt_pk_bf16_f32 v170, v82, v83
	v_cvt_pk_bf16_f32 v171, v84, v85
	v_cvt_pk_bf16_f32 v172, v74, v75
	v_cvt_pk_bf16_f32 v173, v76, v77
	s_nop 1
	v_permlane16_swap_b32 v170, v172
	v_permlane16_swap_b32 v171, v173
	s_nop 1
	global_store_dwordx4 v[184:185], v[170:173], off
	v_mul_f32_e32 v174, 0xbfb8aa3b, v70
	v_mul_f32_e32 v175, 0xbfb8aa3b, v71
	v_mul_f32_e32 v176, 0xbfb8aa3b, v72
	v_mul_f32_e32 v177, 0xbfb8aa3b, v73
	v_mul_f32_e32 v178, 0xbfb8aa3b, v62
	v_mul_f32_e32 v179, 0xbfb8aa3b, v63
	v_mul_f32_e32 v180, 0xbfb8aa3b, v64
	v_mul_f32_e32 v181, 0xbfb8aa3b, v65
	v_exp_f32_e32 v174, v174
	v_exp_f32_e32 v175, v175
	v_exp_f32_e32 v176, v176
	v_exp_f32_e32 v177, v177
	v_exp_f32_e32 v178, v178
	v_exp_f32_e32 v179, v179
	v_exp_f32_e32 v180, v180
	v_exp_f32_e32 v181, v181
	v_add_f32_e32 v174, 1.0, v174
	v_add_f32_e32 v175, 1.0, v175
	v_add_f32_e32 v176, 1.0, v176
	v_add_f32_e32 v177, 1.0, v177
	v_add_f32_e32 v178, 1.0, v178
	v_add_f32_e32 v179, 1.0, v179
	v_add_f32_e32 v180, 1.0, v180
	v_add_f32_e32 v181, 1.0, v181
	v_rcp_f32_e32 v174, v174
	v_rcp_f32_e32 v175, v175
	v_rcp_f32_e32 v176, v176
	v_rcp_f32_e32 v177, v177
	v_rcp_f32_e32 v178, v178
	v_rcp_f32_e32 v179, v179
	v_rcp_f32_e32 v180, v180
	v_rcp_f32_e32 v181, v181
	v_add_u32_e32 v8, 0x2c000, v142
	v_pk_mul_f32 v[70:71], v[70:71], v[174:175]
	v_pk_mul_f32 v[72:73], v[72:73], v[176:177]
	v_pk_mul_f32 v[62:63], v[62:63], v[178:179]
	v_pk_mul_f32 v[64:65], v[64:65], v[180:181]
	v_lshl_add_u64 v[182:183], v[8:9], 1, s[52:53]
	v_pk_mul_f32 v[66:67], v[66:67], v[70:71]
	v_pk_mul_f32 v[68:69], v[68:69], v[72:73]
	v_pk_mul_f32 v[58:59], v[58:59], v[62:63]
	v_pk_mul_f32 v[60:61], v[60:61], v[64:65]
	v_cvt_pk_bf16_f32 v166, v66, v67
	v_cvt_pk_bf16_f32 v167, v68, v69
	v_cvt_pk_bf16_f32 v168, v58, v59
	v_cvt_pk_bf16_f32 v169, v60, v61
; __device__ __forceinline__ float siluf_(float x) { return x * __builtin_amdgcn_rcpf(1.f + __expf(-x)); }
;     ...
;         } else if constexpr (EPI == EPI_SWIGLU) {
; #pragma unroll
;           for (int np = 0; np < 2; np++) {
;             const unsigned hc = ((unsigned)(n0 + wn * 64) >> 1) + np * 16 + fq * 4;
;             const f32x4 g = acc[mi][2 * np], u = acc[mi][2 * np + 1];
;             uint2 o;
;             o.x = pack2(siluf_(g[0]) * u[0], siluf_(g[1]) * u[1]);
;             o.y = pack2(siluf_(g[2]) * u[2], siluf_(g[3]) * u[3]);
;             *(uint2*)(e.b0 + (row * (unsigned)DFF + hc)) = o;
;           }
	s_nop 1
	v_permlane16_swap_b32 v166, v168
	v_permlane16_swap_b32 v167, v169
	s_nop 1
	global_store_dwordx4 v[182:183], v[166:169], off
	v_mul_f32_e32 v174, 0xbfb8aa3b, v54
	v_mul_f32_e32 v175, 0xbfb8aa3b, v55
	v_mul_f32_e32 v176, 0xbfb8aa3b, v56
	v_mul_f32_e32 v177, 0xbfb8aa3b, v57
	v_mul_f32_e32 v178, 0xbfb8aa3b, v46
	v_mul_f32_e32 v179, 0xbfb8aa3b, v47
	v_mul_f32_e32 v180, 0xbfb8aa3b, v48
	v_mul_f32_e32 v181, 0xbfb8aa3b, v49
	v_exp_f32_e32 v174, v174
	v_exp_f32_e32 v175, v175
	v_exp_f32_e32 v176, v176
	v_exp_f32_e32 v177, v177
	v_exp_f32_e32 v178, v178
	v_exp_f32_e32 v179, v179
	v_exp_f32_e32 v180, v180
	v_exp_f32_e32 v181, v181
	v_add_f32_e32 v174, 1.0, v174
	v_add_f32_e32 v175, 1.0, v175
	v_add_f32_e32 v176, 1.0, v176
	v_add_f32_e32 v177, 1.0, v177
	v_add_f32_e32 v178, 1.0, v178
	v_add_f32_e32 v179, 1.0, v179
	v_add_f32_e32 v180, 1.0, v180
	v_add_f32_e32 v181, 1.0, v181
	v_rcp_f32_e32 v174, v174
	v_rcp_f32_e32 v175, v175
	v_rcp_f32_e32 v176, v176
	v_rcp_f32_e32 v177, v177
	v_rcp_f32_e32 v178, v178
	v_rcp_f32_e32 v179, v179
	v_rcp_f32_e32 v180, v180
	v_rcp_f32_e32 v181, v181
	v_add_u32_e32 v8, 0x37000, v142
	v_pk_mul_f32 v[54:55], v[54:55], v[174:175]
	v_pk_mul_f32 v[56:57], v[56:57], v[176:177]
	v_pk_mul_f32 v[46:47], v[46:47], v[178:179]
	v_pk_mul_f32 v[48:49], v[48:49], v[180:181]
	v_lshl_add_u64 v[184:185], v[8:9], 1, s[52:53]
	v_pk_mul_f32 v[50:51], v[50:51], v[54:55]
	v_pk_mul_f32 v[52:53], v[52:53], v[56:57]
	v_pk_mul_f32 v[42:43], v[42:43], v[46:47]
	v_pk_mul_f32 v[44:45], v[44:45], v[48:49]
	v_cvt_pk_bf16_f32 v170, v50, v51
	v_cvt_pk_bf16_f32 v171, v52, v53
	v_cvt_pk_bf16_f32 v172, v42, v43
	v_cvt_pk_bf16_f32 v173, v44, v45
	s_nop 1
	v_permlane16_swap_b32 v170, v172
	v_permlane16_swap_b32 v171, v173
	s_nop 1
	global_store_dwordx4 v[184:185], v[170:173], off
	v_mul_f32_e32 v174, 0xbfb8aa3b, v38
	v_mul_f32_e32 v175, 0xbfb8aa3b, v39
	v_mul_f32_e32 v176, 0xbfb8aa3b, v40
	v_mul_f32_e32 v177, 0xbfb8aa3b, v41
	v_mul_f32_e32 v178, 0xbfb8aa3b, v30
	v_mul_f32_e32 v179, 0xbfb8aa3b, v31
	v_mul_f32_e32 v180, 0xbfb8aa3b, v32
	v_mul_f32_e32 v181, 0xbfb8aa3b, v33
	v_exp_f32_e32 v174, v174
	v_exp_f32_e32 v175, v175
	v_exp_f32_e32 v176, v176
	v_exp_f32_e32 v177, v177
	v_exp_f32_e32 v178, v178
	v_exp_f32_e32 v179, v179
	v_exp_f32_e32 v180, v180
	v_exp_f32_e32 v181, v181
	v_add_f32_e32 v174, 1.0, v174
	v_add_f32_e32 v175, 1.0, v175
	v_add_f32_e32 v176, 1.0, v176
	v_add_f32_e32 v177, 1.0, v177
	v_add_f32_e32 v178, 1.0, v178
	v_add_f32_e32 v179, 1.0, v179
	v_add_f32_e32 v180, 1.0, v180
	v_add_f32_e32 v181, 1.0, v181
	v_rcp_f32_e32 v174, v174
	v_rcp_f32_e32 v175, v175
	v_rcp_f32_e32 v176, v176
	v_rcp_f32_e32 v177, v177
	v_rcp_f32_e32 v178, v178
	v_rcp_f32_e32 v179, v179
	v_rcp_f32_e32 v180, v180
	v_rcp_f32_e32 v181, v181
	v_add_u32_e32 v8, 0x42000, v142
	v_pk_mul_f32 v[38:39], v[38:39], v[174:175]
	v_pk_mul_f32 v[40:41], v[40:41], v[176:177]
	v_pk_mul_f32 v[30:31], v[30:31], v[178:179]
	v_pk_mul_f32 v[32:33], v[32:33], v[180:181]
	v_lshl_add_u64 v[182:183], v[8:9], 1, s[52:53]
	v_pk_mul_f32 v[34:35], v[34:35], v[38:39]
	v_pk_mul_f32 v[36:37], v[36:37], v[40:41]
	v_pk_mul_f32 v[26:27], v[26:27], v[30:31]
	v_pk_mul_f32 v[28:29], v[28:29], v[32:33]
	v_cvt_pk_bf16_f32 v166, v34, v35
	v_cvt_pk_bf16_f32 v167, v36, v37
	v_cvt_pk_bf16_f32 v168, v26, v27
	v_cvt_pk_bf16_f32 v169, v28, v29
	s_nop 1
	v_permlane16_swap_b32 v166, v168
	v_permlane16_swap_b32 v167, v169
	s_nop 1
	global_store_dwordx4 v[182:183], v[166:169], off
	v_mul_f32_e32 v174, 0xbfb8aa3b, v22
	v_mul_f32_e32 v175, 0xbfb8aa3b, v23
	v_mul_f32_e32 v176, 0xbfb8aa3b, v24
	v_mul_f32_e32 v177, 0xbfb8aa3b, v25
	v_mul_f32_e32 v178, 0xbfb8aa3b, v14
	v_mul_f32_e32 v179, 0xbfb8aa3b, v15
	v_mul_f32_e32 v180, 0xbfb8aa3b, v16
	v_mul_f32_e32 v181, 0xbfb8aa3b, v17
	v_exp_f32_e32 v174, v174
	v_exp_f32_e32 v175, v175
	v_exp_f32_e32 v176, v176
	v_exp_f32_e32 v177, v177
	v_exp_f32_e32 v178, v178
	v_exp_f32_e32 v179, v179
	v_exp_f32_e32 v180, v180
	v_exp_f32_e32 v181, v181
	v_add_f32_e32 v174, 1.0, v174
	v_add_f32_e32 v175, 1.0, v175
	v_add_f32_e32 v176, 1.0, v176
	v_add_f32_e32 v177, 1.0, v177
	v_add_f32_e32 v178, 1.0, v178
	v_add_f32_e32 v179, 1.0, v179
	v_add_f32_e32 v180, 1.0, v180
	v_add_f32_e32 v181, 1.0, v181
	v_rcp_f32_e32 v174, v174
	v_rcp_f32_e32 v175, v175
	v_rcp_f32_e32 v176, v176
	v_rcp_f32_e32 v177, v177
	v_rcp_f32_e32 v178, v178
	v_rcp_f32_e32 v179, v179
	v_rcp_f32_e32 v180, v180
	v_rcp_f32_e32 v181, v181
	v_add_u32_e32 v8, 0x4d000, v142
	v_pk_mul_f32 v[22:23], v[22:23], v[174:175]
	v_pk_mul_f32 v[24:25], v[24:25], v[176:177]
	v_pk_mul_f32 v[14:15], v[14:15], v[178:179]
	v_pk_mul_f32 v[16:17], v[16:17], v[180:181]
	v_lshl_add_u64 v[184:185], v[8:9], 1, s[52:53]
	v_pk_mul_f32 v[18:19], v[18:19], v[22:23]
	v_pk_mul_f32 v[20:21], v[20:21], v[24:25]
	v_pk_mul_f32 v[10:11], v[10:11], v[14:15]
	v_pk_mul_f32 v[12:13], v[12:13], v[16:17]
	v_cvt_pk_bf16_f32 v170, v18, v19
	v_cvt_pk_bf16_f32 v171, v20, v21
	v_cvt_pk_bf16_f32 v172, v10, v11
	v_cvt_pk_bf16_f32 v173, v12, v13
	s_nop 1
	v_permlane16_swap_b32 v170, v172
	v_permlane16_swap_b32 v171, v173
	s_nop 1
	global_store_dwordx4 v[184:185], v[170:173], off
	s_setprio 0
	s_add_i32 s6, s6, 1
	s_mov_b64 s[4:5], 0
	s_branch .LBB0_2615
